# scan: P^T causal-mask code reduced to one compare per element (direction folded into indices), emit blocks regenerated with dpp-add reductions and saddr stores; plus earlier edits; bit-identical outpu
# speedup vs baseline: 1.0085x; 1.0062x over previous
.LBB0_500:
	v_lshlrev_b32_e32 v141, 2, v140
	v_and_b32_e32 v221, 31, v140
	v_bfe_u32 v130, v140, 5, 1
	v_and_b32_e32 v100, 12, v141
	v_bfe_u32 v99, v140, 2, 2
	v_lshlrev_b32_e32 v98, 8, v221
	v_bitop3_b32 v66, v100, v130, v99 bitop3:0x36
	v_lshlrev_b32_e32 v243, 4, v66
	v_add_u32_e32 v114, s49, v98
	v_add_u32_e32 v248, v114, v243
	ds_read_b128 v[66:69], v248 offset:32768
	v_add_u32_e32 v249, 0, v98
	v_add_u32_e32 v115, s97, v249
	v_add_u32_e32 v70, v115, v243
	ds_read_b128 v[70:73], v70
	v_xor_b32_e32 v245, 32, v243
	v_add_u32_e32 v247, v114, v245
	ds_read_b128 v[102:105], v247 offset:32768
	v_add_u32_e32 v101, v115, v245
	ds_read_b128 v[106:109], v101
	s_waitcnt lgkmcnt(0)
	v_mfma_f32_32x32x16_bf16 v[66:81], v[66:69], v[70:73], 0
	v_xor_b32_e32 v241, 64, v243
	v_add_u32_e32 v242, v114, v241
	v_add_u32_e32 v101, v115, v241
	v_xor_b32_e32 v226, 0x60, v243
	v_xor_b32_e32 v223, 0x80, v243
	v_add_u32_e32 v238, v114, v226
	v_add_u32_e32 v224, v114, v223
	v_mfma_f32_32x32x16_bf16 v[66:81], v[102:105], v[106:109], v[66:81]
	ds_read_b128 v[102:105], v242 offset:32768
	ds_read_b128 v[106:109], v101
	ds_read_b128 v[110:113], v224 offset:32768
	v_add_u32_e32 v101, v115, v226
	v_xor_b32_e32 v225, 0xa0, v243
	v_add_u32_e32 v227, v114, v225
	v_xor_b32_e32 v239, 0xc0, v243
	s_waitcnt lgkmcnt(0)
	v_mfma_f32_32x32x16_bf16 v[66:81], v[102:105], v[106:109], v[66:81]
	ds_read_b128 v[102:105], v238 offset:32768
	ds_read_b128 v[106:109], v101
	v_lshlrev_b32_e32 v101, 2, v155
	v_xor_b32_e32 v157, 0x80, v101
	v_add_u32_e32 v101, v115, v225
	v_add_u32_e32 v240, v114, v239
	v_xor_b32_e32 v244, 0xe0, v243
	s_waitcnt lgkmcnt(0)
	v_mfma_f32_32x32x16_bf16 v[66:81], v[102:105], v[106:109], v[66:81]
	v_add_u32_e32 v102, v115, v223
	ds_read_b128 v[102:105], v102
	ds_read_b128 v[106:109], v227 offset:32768
	v_add_u32_e32 v246, v114, v244
	v_lshl_add_u32 v204, v130, 4, s63
	v_lshl_or_b32 v217, v130, 2, s62
	v_xnor_b32_e32 v217, s4, v217
	v_xor_b32_e32 v222, 1, v217
	s_waitcnt lgkmcnt(0)
	v_mfma_f32_32x32x16_bf16 v[66:81], v[110:113], v[102:105], v[66:81]
	ds_read_b128 v[102:105], v101
	ds_read_b128 v[110:113], v240 offset:32768
	v_or_b32_e32 v101, s75, v221
	v_lshl_add_u32 v116, v101, 2, 0
	v_xor_b32_e32 v220, 2, v217
	v_xor_b32_e32 v218, 3, v217
	s_waitcnt lgkmcnt(0)
	v_mfma_f32_32x32x16_bf16 v[66:81], v[106:109], v[102:105], v[66:81]
	v_add_u32_e32 v102, v115, v239
	ds_read_b128 v[102:105], v102
	ds_read_b128 v[106:109], v246 offset:32768
	v_xor_b32_e32 v216, 8, v217
	v_xor_b32_e32 v215, 9, v217
	s_waitcnt lgkmcnt(0)
	v_mfma_f32_32x32x16_bf16 v[66:81], v[110:113], v[102:105], v[66:81]
	v_add_u32_e32 v102, v115, v244
	ds_read_b128 v[102:105], v102
	v_add_u32_e32 v115, 0x20200, v116
	ds_read_b128 v[110:113], v204
	ds_read_b32 v115, v115
	v_xor_b32_e32 v214, 10, v217
	v_xor_b32_e32 v210, 11, v217
	s_waitcnt lgkmcnt(0)
	v_mfma_f32_32x32x16_bf16 v[66:81], v[106:109], v[102:105], v[66:81]
	v_xnor_b32_e32 v117, s4, v101
	ds_read_b128 v[120:123], v204 offset:32
	ds_read_b128 v[124:127], v204 offset:64
	ds_read_b128 v[132:135], v204 offset:96
	v_xor_b32_e32 v209, 16, v217
	v_xor_b32_e32 v211, 17, v217
	v_xor_b32_e32 v212, 18, v217
	v_xor_b32_e32 v213, 19, v217
	v_xor_b32_e32 v208, 24, v217
	v_xor_b32_e32 v207, 25, v217
	v_xor_b32_e32 v206, 26, v217
	v_xor_b32_e32 v205, 27, v217
	v_cmp_eq_u32_e64 s[10:11], 0, v130
	s_waitcnt lgkmcnt(3)
	v_sub_f32_e32 v118, v110, v115
	v_exp_f32_e32 v118, v118
	v_cmp_le_u32_e32 vcc, v217, v117
	v_sub_f32_e32 v119, v111, v115
	v_exp_f32_e32 v119, v119
	v_cmp_le_u32_e64 s[2:3], v222, v117
	v_cndmask_b32_e32 v118, 0, v118, vcc
	v_mul_f32_e32 v66, v66, v118
	v_sub_f32_e32 v118, v112, v115
	v_exp_f32_e32 v118, v118
	v_cmp_le_u32_e32 vcc, v220, v117
	v_cndmask_b32_e64 v119, 0, v119, s[2:3]
	v_mul_f32_e32 v67, v67, v119
	v_sub_f32_e32 v119, v113, v115
	v_exp_f32_e32 v119, v119
	v_cmp_le_u32_e64 s[2:3], v218, v117
	v_cndmask_b32_e32 v118, 0, v118, vcc
	v_mul_f32_e32 v68, v68, v118
	s_waitcnt lgkmcnt(2)
	v_sub_f32_e32 v118, v120, v115
	v_exp_f32_e32 v118, v118
	v_cmp_le_u32_e32 vcc, v216, v117
	v_cndmask_b32_e64 v119, 0, v119, s[2:3]
	v_mul_f32_e32 v69, v69, v119
	v_sub_f32_e32 v119, v121, v115
	v_exp_f32_e32 v119, v119
	v_cmp_le_u32_e64 s[2:3], v215, v117
	v_cndmask_b32_e32 v118, 0, v118, vcc
	v_mul_f32_e32 v70, v70, v118
	v_sub_f32_e32 v118, v122, v115
	v_exp_f32_e32 v118, v118
	v_cmp_le_u32_e32 vcc, v214, v117
	v_cndmask_b32_e64 v119, 0, v119, s[2:3]
	v_mul_f32_e32 v71, v71, v119
	v_sub_f32_e32 v119, v123, v115
	v_exp_f32_e32 v119, v119
	v_cmp_le_u32_e64 s[2:3], v210, v117
	v_cndmask_b32_e32 v118, 0, v118, vcc
	v_mul_f32_e32 v102, v72, v118
	s_waitcnt lgkmcnt(1)
	v_sub_f32_e32 v118, v124, v115
	v_exp_f32_e32 v118, v118
	v_cmp_le_u32_e32 vcc, v209, v117
	v_cndmask_b32_e64 v119, 0, v119, s[2:3]
	v_mul_f32_e32 v73, v73, v119
	v_sub_f32_e32 v119, v125, v115
	v_exp_f32_e32 v119, v119
	v_cmp_le_u32_e64 s[2:3], v211, v117
	v_cndmask_b32_e32 v118, 0, v118, vcc
	v_mul_f32_e32 v74, v74, v118
	v_sub_f32_e32 v118, v126, v115
	v_exp_f32_e32 v118, v118
	v_cmp_le_u32_e32 vcc, v212, v117
	v_cndmask_b32_e64 v119, 0, v119, s[2:3]
	v_mul_f32_e32 v75, v75, v119
	v_sub_f32_e32 v119, v127, v115
	v_exp_f32_e32 v119, v119
	v_cmp_le_u32_e64 s[2:3], v213, v117
	v_cndmask_b32_e32 v118, 0, v118, vcc
	v_mul_f32_e32 v76, v76, v118
	s_waitcnt lgkmcnt(0)
	v_sub_f32_e32 v118, v132, v115
	v_exp_f32_e32 v118, v118
	v_cmp_le_u32_e32 vcc, v208, v117
	v_cndmask_b32_e64 v119, 0, v119, s[2:3]
	v_mul_f32_e32 v77, v77, v119
	v_sub_f32_e32 v119, v133, v115
	v_exp_f32_e32 v119, v119
	v_cmp_le_u32_e64 s[2:3], v207, v117
	v_cndmask_b32_e32 v118, 0, v118, vcc
	v_mul_f32_e32 v78, v78, v118
	v_sub_f32_e32 v118, v134, v115
	v_exp_f32_e32 v118, v118
	v_cmp_le_u32_e32 vcc, v206, v117
	v_cndmask_b32_e64 v119, 0, v119, s[2:3]
	v_mul_f32_e32 v79, v79, v119
	v_sub_f32_e32 v119, v135, v115
	v_exp_f32_e32 v119, v119
	v_cmp_le_u32_e64 s[2:3], v205, v117
	v_cndmask_b32_e32 v118, 0, v118, vcc
	v_mul_f32_e32 v80, v80, v118
	v_cndmask_b32_e64 v119, 0, v119, s[2:3]
	v_mul_f32_e32 v81, v81, v119
	s_and_b64 vcc, exec, s[6:7]
	s_cbranch_vccnz .LBB0_504
	v_add_f32_e32 v72, 0, v66
	v_add_f32_e32 v72, v67, v72
	v_add_f32_e32 v72, v68, v72
	v_add_f32_e32 v72, v69, v72
	v_add_f32_e32 v72, v70, v72
	v_add_f32_e32 v72, v71, v72
	v_add_f32_e32 v72, v102, v72
	v_add_f32_e32 v72, v73, v72
	v_add_f32_e32 v72, v74, v72
	v_add_f32_e32 v72, v75, v72
	v_add_f32_e32 v72, v76, v72
	v_add_f32_e32 v72, v77, v72
	v_add_f32_e32 v72, v78, v72
	v_add_f32_e32 v72, v79, v72
	v_add_f32_e32 v72, v80, v72
	v_add_f32_e32 v72, v81, v72
	ds_bpermute_b32 v103, v157, v72
	s_and_saveexec_b64 s[2:3], s[10:11]
	s_cbranch_execz .LBB0_503
	v_readlane_b32 s8, v254, 52
	s_waitcnt lgkmcnt(0)
	v_add_f32_e32 v72, v72, v103
	v_lshl_add_u32 v101, v101, 2, s8
	ds_write_b32 v101, v72

.LBB0_510:
	s_cmp_gt_u32 s41, 17
	v_and_b32_e32 v132, 16, v140
	s_cselect_b64 s[26:27], -1, 0
	v_cmp_eq_u32_e32 vcc, 0, v132
	s_lshl_b64 s[14:15], s[16:17], 12
	v_lshlrev_b32_e32 v131, 1, v221
	v_cndmask_b32_e32 v132, v235, v236, vcc
	s_add_u32 s20, s42, s14
	v_cmp_eq_u32_e64 s[8:9], 0, v156
	v_add_u32_e32 v177, s45, v132
	v_lshl_or_b32 v144, v130, 14, v131
	s_addc_u32 s21, s43, s15
	s_mov_b64 s[14:15], -1
	s_and_b64 vcc, exec, s[26:27]
	s_cbranch_vccz .LBB0_520
	s_waitcnt vmcnt(0)
	v_add_u32_e32 v148, v177, v164
	v_lshlrev_b32_e32 v132, 16, v94
	v_and_b32_e32 v133, 0xffff0000, v94
	v_lshlrev_b32_e32 v134, 16, v95
	v_and_b32_e32 v135, 0xffff0000, v95
	v_pk_add_f32 v[132:133], v[66:67], v[132:133]
	v_pk_add_f32 v[134:135], v[68:69], v[134:135]
	v_add_u32_e32 v142, 0x1000, v144
	v_add_u32_e32 v143, 0x3000, v144
	v_pk_mul_f32 v[196:197], v[132:133], v[132:133]
	v_pk_mul_f32 v[198:199], v[134:135], v[134:135]
	v_cvt_pk_bf16_f32 v136, v132, s0
	v_cvt_pk_bf16_f32 v137, v133, s0
	v_mov_b32_dpp v250, v196 quad_perm:[1,0,3,2] row_mask:0xf bank_mask:0xf
	v_mov_b32_dpp v251, v197 quad_perm:[1,0,3,2] row_mask:0xf bank_mask:0xf
	v_mov_b32_dpp v252, v198 quad_perm:[1,0,3,2] row_mask:0xf bank_mask:0xf
	v_mov_b32_dpp v253, v199 quad_perm:[1,0,3,2] row_mask:0xf bank_mask:0xf
	global_store_short v142, v136, s[20:21] offset:-4096
	global_store_short v142, v137, s[20:21]
	v_pk_fma_f32 v[196:197], v[132:133], v[132:133], v[250:251]
	v_pk_fma_f32 v[198:199], v[134:135], v[134:135], v[252:253]
	v_cvt_pk_bf16_f32 v136, v134, s0
	v_cvt_pk_bf16_f32 v137, v135, s0
	v_add_f32_dpp v196, v196, v196 quad_perm:[2,3,0,1] row_mask:0xf bank_mask:0xf
	v_add_f32_dpp v197, v197, v197 quad_perm:[2,3,0,1] row_mask:0xf bank_mask:0xf
	v_add_f32_dpp v198, v198, v198 quad_perm:[2,3,0,1] row_mask:0xf bank_mask:0xf
	v_add_f32_dpp v199, v199, v199 quad_perm:[2,3,0,1] row_mask:0xf bank_mask:0xf
	global_store_short v143, v136, s[20:21] offset:-4096
	global_store_short v143, v137, s[20:21]
	v_add_f32_dpp v196, v196, v196 row_half_mirror row_mask:0xf bank_mask:0xf
	v_add_f32_dpp v197, v197, v197 row_half_mirror row_mask:0xf bank_mask:0xf
	v_add_f32_dpp v198, v198, v198 row_half_mirror row_mask:0xf bank_mask:0xf
	v_add_f32_dpp v199, v199, v199 row_half_mirror row_mask:0xf bank_mask:0xf
	v_add_f32_dpp v196, v196, v196 row_mirror row_mask:0xf bank_mask:0xf
	v_add_f32_dpp v197, v197, v197 row_mirror row_mask:0xf bank_mask:0xf
	v_add_f32_dpp v198, v198, v198 row_mirror row_mask:0xf bank_mask:0xf
	v_add_f32_dpp v199, v199, v199 row_mirror row_mask:0xf bank_mask:0xf
	s_and_saveexec_b64 s[14:15], s[8:9]
	ds_write_b128 v148, v[196:199]
	s_or_b64 exec, exec, s[14:15]
	v_lshlrev_b32_e32 v132, 16, v96
	v_and_b32_e32 v133, 0xffff0000, v96
	v_lshlrev_b32_e32 v134, 16, v97
	v_and_b32_e32 v135, 0xffff0000, v97
	v_pk_add_f32 v[132:133], v[70:71], v[132:133]
	v_pk_add_f32 v[134:135], v[72:73], v[134:135]
	v_add_u32_e32 v142, 0x9000, v144
	v_add_u32_e32 v143, 0xb000, v144
	v_pk_mul_f32 v[196:197], v[132:133], v[132:133]
	v_pk_mul_f32 v[198:199], v[134:135], v[134:135]
	v_cvt_pk_bf16_f32 v136, v132, s0
	v_cvt_pk_bf16_f32 v137, v133, s0
	v_mov_b32_dpp v250, v196 quad_perm:[1,0,3,2] row_mask:0xf bank_mask:0xf
	v_mov_b32_dpp v251, v197 quad_perm:[1,0,3,2] row_mask:0xf bank_mask:0xf
	v_mov_b32_dpp v252, v198 quad_perm:[1,0,3,2] row_mask:0xf bank_mask:0xf
	v_mov_b32_dpp v253, v199 quad_perm:[1,0,3,2] row_mask:0xf bank_mask:0xf
	global_store_short v142, v136, s[20:21] offset:-4096
	global_store_short v142, v137, s[20:21]
	v_pk_fma_f32 v[196:197], v[132:133], v[132:133], v[250:251]
	v_pk_fma_f32 v[198:199], v[134:135], v[134:135], v[252:253]
	v_cvt_pk_bf16_f32 v136, v134, s0
	v_cvt_pk_bf16_f32 v137, v135, s0
	v_add_f32_dpp v196, v196, v196 quad_perm:[2,3,0,1] row_mask:0xf bank_mask:0xf
	v_add_f32_dpp v197, v197, v197 quad_perm:[2,3,0,1] row_mask:0xf bank_mask:0xf
	v_add_f32_dpp v198, v198, v198 quad_perm:[2,3,0,1] row_mask:0xf bank_mask:0xf
	v_add_f32_dpp v199, v199, v199 quad_perm:[2,3,0,1] row_mask:0xf bank_mask:0xf
	global_store_short v143, v136, s[20:21] offset:-4096
	global_store_short v143, v137, s[20:21]
	v_add_f32_dpp v196, v196, v196 row_half_mirror row_mask:0xf bank_mask:0xf
	v_add_f32_dpp v197, v197, v197 row_half_mirror row_mask:0xf bank_mask:0xf
	v_add_f32_dpp v198, v198, v198 row_half_mirror row_mask:0xf bank_mask:0xf
	v_add_f32_dpp v199, v199, v199 row_half_mirror row_mask:0xf bank_mask:0xf
	v_add_f32_dpp v196, v196, v196 row_mirror row_mask:0xf bank_mask:0xf
	v_add_f32_dpp v197, v197, v197 row_mirror row_mask:0xf bank_mask:0xf
	v_add_f32_dpp v198, v198, v198 row_mirror row_mask:0xf bank_mask:0xf
	v_add_f32_dpp v199, v199, v199 row_mirror row_mask:0xf bank_mask:0xf
	s_and_saveexec_b64 s[14:15], s[8:9]
	ds_write_b128 v148, v[196:199] offset:32
	s_or_b64 exec, exec, s[14:15]
	v_lshlrev_b32_e32 v132, 16, v90
	v_and_b32_e32 v133, 0xffff0000, v90
	v_lshlrev_b32_e32 v134, 16, v91
	v_and_b32_e32 v135, 0xffff0000, v91
	v_pk_add_f32 v[132:133], v[74:75], v[132:133]
	v_pk_add_f32 v[134:135], v[76:77], v[134:135]
	v_add_u32_e32 v142, 0x11000, v144
	v_add_u32_e32 v143, 0x13000, v144
	v_pk_mul_f32 v[196:197], v[132:133], v[132:133]
	v_pk_mul_f32 v[198:199], v[134:135], v[134:135]
	v_cvt_pk_bf16_f32 v136, v132, s0
	v_cvt_pk_bf16_f32 v137, v133, s0
	v_mov_b32_dpp v250, v196 quad_perm:[1,0,3,2] row_mask:0xf bank_mask:0xf
	v_mov_b32_dpp v251, v197 quad_perm:[1,0,3,2] row_mask:0xf bank_mask:0xf
	v_mov_b32_dpp v252, v198 quad_perm:[1,0,3,2] row_mask:0xf bank_mask:0xf
	v_mov_b32_dpp v253, v199 quad_perm:[1,0,3,2] row_mask:0xf bank_mask:0xf
	global_store_short v142, v136, s[20:21] offset:-4096
	global_store_short v142, v137, s[20:21]
	v_pk_fma_f32 v[196:197], v[132:133], v[132:133], v[250:251]
	v_pk_fma_f32 v[198:199], v[134:135], v[134:135], v[252:253]
	v_cvt_pk_bf16_f32 v136, v134, s0
	v_cvt_pk_bf16_f32 v137, v135, s0
	v_add_f32_dpp v196, v196, v196 quad_perm:[2,3,0,1] row_mask:0xf bank_mask:0xf
	v_add_f32_dpp v197, v197, v197 quad_perm:[2,3,0,1] row_mask:0xf bank_mask:0xf
	v_add_f32_dpp v198, v198, v198 quad_perm:[2,3,0,1] row_mask:0xf bank_mask:0xf
	v_add_f32_dpp v199, v199, v199 quad_perm:[2,3,0,1] row_mask:0xf bank_mask:0xf
	global_store_short v143, v136, s[20:21] offset:-4096
	global_store_short v143, v137, s[20:21]
	v_add_f32_dpp v196, v196, v196 row_half_mirror row_mask:0xf bank_mask:0xf
	v_add_f32_dpp v197, v197, v197 row_half_mirror row_mask:0xf bank_mask:0xf
	v_add_f32_dpp v198, v198, v198 row_half_mirror row_mask:0xf bank_mask:0xf
	v_add_f32_dpp v199, v199, v199 row_half_mirror row_mask:0xf bank_mask:0xf
	v_add_f32_dpp v196, v196, v196 row_mirror row_mask:0xf bank_mask:0xf
	v_add_f32_dpp v197, v197, v197 row_mirror row_mask:0xf bank_mask:0xf
	v_add_f32_dpp v198, v198, v198 row_mirror row_mask:0xf bank_mask:0xf
	v_add_f32_dpp v199, v199, v199 row_mirror row_mask:0xf bank_mask:0xf
	s_and_saveexec_b64 s[14:15], s[8:9]
	ds_write_b128 v148, v[196:199] offset:64
	s_or_b64 exec, exec, s[14:15]
	v_lshlrev_b32_e32 v132, 16, v92
	v_and_b32_e32 v133, 0xffff0000, v92
	v_lshlrev_b32_e32 v134, 16, v93
	v_and_b32_e32 v135, 0xffff0000, v93
	v_pk_add_f32 v[132:133], v[78:79], v[132:133]
	v_pk_add_f32 v[134:135], v[80:81], v[134:135]
	v_add_u32_e32 v142, 0x19000, v144
	v_add_u32_e32 v143, 0x1b000, v144
	v_pk_mul_f32 v[196:197], v[132:133], v[132:133]
	v_pk_mul_f32 v[198:199], v[134:135], v[134:135]
	v_cvt_pk_bf16_f32 v136, v132, s0
	v_cvt_pk_bf16_f32 v137, v133, s0
	v_mov_b32_dpp v250, v196 quad_perm:[1,0,3,2] row_mask:0xf bank_mask:0xf
	v_mov_b32_dpp v251, v197 quad_perm:[1,0,3,2] row_mask:0xf bank_mask:0xf
	v_mov_b32_dpp v252, v198 quad_perm:[1,0,3,2] row_mask:0xf bank_mask:0xf
	v_mov_b32_dpp v253, v199 quad_perm:[1,0,3,2] row_mask:0xf bank_mask:0xf
	global_store_short v142, v136, s[20:21] offset:-4096
	global_store_short v142, v137, s[20:21]
	v_pk_fma_f32 v[196:197], v[132:133], v[132:133], v[250:251]
	v_pk_fma_f32 v[198:199], v[134:135], v[134:135], v[252:253]
	v_cvt_pk_bf16_f32 v136, v134, s0
	v_cvt_pk_bf16_f32 v137, v135, s0
	v_add_f32_dpp v196, v196, v196 quad_perm:[2,3,0,1] row_mask:0xf bank_mask:0xf
	v_add_f32_dpp v197, v197, v197 quad_perm:[2,3,0,1] row_mask:0xf bank_mask:0xf
	v_add_f32_dpp v198, v198, v198 quad_perm:[2,3,0,1] row_mask:0xf bank_mask:0xf
	v_add_f32_dpp v199, v199, v199 quad_perm:[2,3,0,1] row_mask:0xf bank_mask:0xf
	global_store_short v143, v136, s[20:21] offset:-4096
	global_store_short v143, v137, s[20:21]
	v_add_f32_dpp v196, v196, v196 row_half_mirror row_mask:0xf bank_mask:0xf
	v_add_f32_dpp v197, v197, v197 row_half_mirror row_mask:0xf bank_mask:0xf
	v_add_f32_dpp v198, v198, v198 row_half_mirror row_mask:0xf bank_mask:0xf
	v_add_f32_dpp v199, v199, v199 row_half_mirror row_mask:0xf bank_mask:0xf
	v_add_f32_dpp v196, v196, v196 row_mirror row_mask:0xf bank_mask:0xf
	v_add_f32_dpp v197, v197, v197 row_mirror row_mask:0xf bank_mask:0xf
	v_add_f32_dpp v198, v198, v198 row_mirror row_mask:0xf bank_mask:0xf
	v_add_f32_dpp v199, v199, v199 row_mirror row_mask:0xf bank_mask:0xf
	s_and_saveexec_b64 s[14:15], s[8:9]
	ds_write_b128 v148, v[196:199] offset:96
	s_or_b64 exec, exec, s[14:15]
	s_mov_b64 s[14:15], 0

.LBB0_524:
	v_cndmask_b32_e64 v130, 0, 1, s[26:27]
	v_cmp_ne_u32_e64 s[14:15], 1, v130
	s_andn2_b64 vcc, exec, s[26:27]
	s_mov_b64 s[2:3], -1
	s_cbranch_vccnz .LBB0_534
	s_waitcnt vmcnt(15)
	v_add_u32_e32 v190, v177, v164
	v_lshlrev_b32_e32 v132, 16, v86
	v_and_b32_e32 v133, 0xffff0000, v86
	v_lshlrev_b32_e32 v134, 16, v87
	v_and_b32_e32 v135, 0xffff0000, v87
	v_pk_add_f32 v[132:133], v[66:67], v[132:133]
	v_pk_add_f32 v[134:135], v[68:69], v[134:135]
	v_add_u32_e32 v130, 0x21000, v144
	v_add_u32_e32 v131, 0x23000, v144
	v_pk_mul_f32 v[250:251], v[132:133], v[132:133]
	v_pk_mul_f32 v[252:253], v[134:135], v[134:135]
	v_cvt_pk_bf16_f32 v196, v132, s0
	v_cvt_pk_bf16_f32 v197, v133, s0
	v_mov_b32_dpp v136, v250 quad_perm:[1,0,3,2] row_mask:0xf bank_mask:0xf
	v_mov_b32_dpp v137, v251 quad_perm:[1,0,3,2] row_mask:0xf bank_mask:0xf
	v_mov_b32_dpp v148, v252 quad_perm:[1,0,3,2] row_mask:0xf bank_mask:0xf
	v_mov_b32_dpp v149, v253 quad_perm:[1,0,3,2] row_mask:0xf bank_mask:0xf
	global_store_short v130, v196, s[20:21] offset:-4096
	global_store_short v130, v197, s[20:21]
	v_pk_fma_f32 v[250:251], v[132:133], v[132:133], v[136:137]
	v_pk_fma_f32 v[252:253], v[134:135], v[134:135], v[148:149]
	v_cvt_pk_bf16_f32 v196, v134, s0
	v_cvt_pk_bf16_f32 v197, v135, s0
	v_add_f32_dpp v250, v250, v250 quad_perm:[2,3,0,1] row_mask:0xf bank_mask:0xf
	v_add_f32_dpp v251, v251, v251 quad_perm:[2,3,0,1] row_mask:0xf bank_mask:0xf
	v_add_f32_dpp v252, v252, v252 quad_perm:[2,3,0,1] row_mask:0xf bank_mask:0xf
	v_add_f32_dpp v253, v253, v253 quad_perm:[2,3,0,1] row_mask:0xf bank_mask:0xf
	global_store_short v131, v196, s[20:21] offset:-4096
	global_store_short v131, v197, s[20:21]
	v_add_f32_dpp v250, v250, v250 row_half_mirror row_mask:0xf bank_mask:0xf
	v_add_f32_dpp v251, v251, v251 row_half_mirror row_mask:0xf bank_mask:0xf
	v_add_f32_dpp v252, v252, v252 row_half_mirror row_mask:0xf bank_mask:0xf
	v_add_f32_dpp v253, v253, v253 row_half_mirror row_mask:0xf bank_mask:0xf
	v_add_f32_dpp v250, v250, v250 row_mirror row_mask:0xf bank_mask:0xf
	v_add_f32_dpp v251, v251, v251 row_mirror row_mask:0xf bank_mask:0xf
	v_add_f32_dpp v252, v252, v252 row_mirror row_mask:0xf bank_mask:0xf
	v_add_f32_dpp v253, v253, v253 row_mirror row_mask:0xf bank_mask:0xf
	s_and_saveexec_b64 s[2:3], s[8:9]
	ds_write_b128 v190, v[250:253] offset:128
	s_or_b64 exec, exec, s[2:3]
	v_lshlrev_b32_e32 v132, 16, v88
	v_and_b32_e32 v133, 0xffff0000, v88
	v_lshlrev_b32_e32 v134, 16, v89
	v_and_b32_e32 v135, 0xffff0000, v89
	v_pk_add_f32 v[132:133], v[70:71], v[132:133]
	v_pk_add_f32 v[134:135], v[72:73], v[134:135]
	v_add_u32_e32 v130, 0x29000, v144
	v_add_u32_e32 v131, 0x2b000, v144
	v_pk_mul_f32 v[250:251], v[132:133], v[132:133]
	v_pk_mul_f32 v[252:253], v[134:135], v[134:135]
	v_cvt_pk_bf16_f32 v196, v132, s0
	v_cvt_pk_bf16_f32 v197, v133, s0
	v_mov_b32_dpp v136, v250 quad_perm:[1,0,3,2] row_mask:0xf bank_mask:0xf
	v_mov_b32_dpp v137, v251 quad_perm:[1,0,3,2] row_mask:0xf bank_mask:0xf
	v_mov_b32_dpp v148, v252 quad_perm:[1,0,3,2] row_mask:0xf bank_mask:0xf
	v_mov_b32_dpp v149, v253 quad_perm:[1,0,3,2] row_mask:0xf bank_mask:0xf
	global_store_short v130, v196, s[20:21] offset:-4096
	global_store_short v130, v197, s[20:21]
	v_pk_fma_f32 v[250:251], v[132:133], v[132:133], v[136:137]
	v_pk_fma_f32 v[252:253], v[134:135], v[134:135], v[148:149]
	v_cvt_pk_bf16_f32 v196, v134, s0
	v_cvt_pk_bf16_f32 v197, v135, s0
	v_add_f32_dpp v250, v250, v250 quad_perm:[2,3,0,1] row_mask:0xf bank_mask:0xf
	v_add_f32_dpp v251, v251, v251 quad_perm:[2,3,0,1] row_mask:0xf bank_mask:0xf
	v_add_f32_dpp v252, v252, v252 quad_perm:[2,3,0,1] row_mask:0xf bank_mask:0xf
	v_add_f32_dpp v253, v253, v253 quad_perm:[2,3,0,1] row_mask:0xf bank_mask:0xf
	global_store_short v131, v196, s[20:21] offset:-4096
	global_store_short v131, v197, s[20:21]
	v_add_f32_dpp v250, v250, v250 row_half_mirror row_mask:0xf bank_mask:0xf
	v_add_f32_dpp v251, v251, v251 row_half_mirror row_mask:0xf bank_mask:0xf
	v_add_f32_dpp v252, v252, v252 row_half_mirror row_mask:0xf bank_mask:0xf
	v_add_f32_dpp v253, v253, v253 row_half_mirror row_mask:0xf bank_mask:0xf
	v_add_f32_dpp v250, v250, v250 row_mirror row_mask:0xf bank_mask:0xf
	v_add_f32_dpp v251, v251, v251 row_mirror row_mask:0xf bank_mask:0xf
	v_add_f32_dpp v252, v252, v252 row_mirror row_mask:0xf bank_mask:0xf
	v_add_f32_dpp v253, v253, v253 row_mirror row_mask:0xf bank_mask:0xf
	s_and_saveexec_b64 s[2:3], s[8:9]
	ds_write_b128 v190, v[250:253] offset:160
	s_or_b64 exec, exec, s[2:3]
	v_lshlrev_b32_e32 v132, 16, v82
	v_and_b32_e32 v133, 0xffff0000, v82
	v_lshlrev_b32_e32 v134, 16, v83
	v_and_b32_e32 v135, 0xffff0000, v83
	v_pk_add_f32 v[132:133], v[74:75], v[132:133]
	v_pk_add_f32 v[134:135], v[76:77], v[134:135]
	v_add_u32_e32 v130, 0x31000, v144
	v_add_u32_e32 v131, 0x33000, v144
	v_pk_mul_f32 v[250:251], v[132:133], v[132:133]
	v_pk_mul_f32 v[252:253], v[134:135], v[134:135]
	v_cvt_pk_bf16_f32 v196, v132, s0
	v_cvt_pk_bf16_f32 v197, v133, s0
	v_mov_b32_dpp v136, v250 quad_perm:[1,0,3,2] row_mask:0xf bank_mask:0xf
	v_mov_b32_dpp v137, v251 quad_perm:[1,0,3,2] row_mask:0xf bank_mask:0xf
	v_mov_b32_dpp v148, v252 quad_perm:[1,0,3,2] row_mask:0xf bank_mask:0xf
	v_mov_b32_dpp v149, v253 quad_perm:[1,0,3,2] row_mask:0xf bank_mask:0xf
	global_store_short v130, v196, s[20:21] offset:-4096
	global_store_short v130, v197, s[20:21]
	v_pk_fma_f32 v[250:251], v[132:133], v[132:133], v[136:137]
	v_pk_fma_f32 v[252:253], v[134:135], v[134:135], v[148:149]
	v_cvt_pk_bf16_f32 v196, v134, s0
	v_cvt_pk_bf16_f32 v197, v135, s0
	v_add_f32_dpp v250, v250, v250 quad_perm:[2,3,0,1] row_mask:0xf bank_mask:0xf
	v_add_f32_dpp v251, v251, v251 quad_perm:[2,3,0,1] row_mask:0xf bank_mask:0xf
	v_add_f32_dpp v252, v252, v252 quad_perm:[2,3,0,1] row_mask:0xf bank_mask:0xf
	v_add_f32_dpp v253, v253, v253 quad_perm:[2,3,0,1] row_mask:0xf bank_mask:0xf
	global_store_short v131, v196, s[20:21] offset:-4096
	global_store_short v131, v197, s[20:21]
	v_add_f32_dpp v250, v250, v250 row_half_mirror row_mask:0xf bank_mask:0xf
	v_add_f32_dpp v251, v251, v251 row_half_mirror row_mask:0xf bank_mask:0xf
	v_add_f32_dpp v252, v252, v252 row_half_mirror row_mask:0xf bank_mask:0xf
	v_add_f32_dpp v253, v253, v253 row_half_mirror row_mask:0xf bank_mask:0xf
	v_add_f32_dpp v250, v250, v250 row_mirror row_mask:0xf bank_mask:0xf
	v_add_f32_dpp v251, v251, v251 row_mirror row_mask:0xf bank_mask:0xf
	v_add_f32_dpp v252, v252, v252 row_mirror row_mask:0xf bank_mask:0xf
	v_add_f32_dpp v253, v253, v253 row_mirror row_mask:0xf bank_mask:0xf
	s_and_saveexec_b64 s[2:3], s[8:9]
	ds_write_b128 v190, v[250:253] offset:192
	s_or_b64 exec, exec, s[2:3]
	v_lshlrev_b32_e32 v132, 16, v84
	v_and_b32_e32 v133, 0xffff0000, v84
	v_lshlrev_b32_e32 v134, 16, v85
	v_and_b32_e32 v135, 0xffff0000, v85
	v_pk_add_f32 v[132:133], v[78:79], v[132:133]
	v_pk_add_f32 v[134:135], v[80:81], v[134:135]
	v_add_u32_e32 v130, 0x39000, v144
	v_add_u32_e32 v131, 0x3b000, v144
	v_pk_mul_f32 v[250:251], v[132:133], v[132:133]
	v_pk_mul_f32 v[252:253], v[134:135], v[134:135]
	v_cvt_pk_bf16_f32 v196, v132, s0
	v_cvt_pk_bf16_f32 v197, v133, s0
	v_mov_b32_dpp v136, v250 quad_perm:[1,0,3,2] row_mask:0xf bank_mask:0xf
	v_mov_b32_dpp v137, v251 quad_perm:[1,0,3,2] row_mask:0xf bank_mask:0xf
	v_mov_b32_dpp v148, v252 quad_perm:[1,0,3,2] row_mask:0xf bank_mask:0xf
	v_mov_b32_dpp v149, v253 quad_perm:[1,0,3,2] row_mask:0xf bank_mask:0xf
	global_store_short v130, v196, s[20:21] offset:-4096
	global_store_short v130, v197, s[20:21]
	v_pk_fma_f32 v[250:251], v[132:133], v[132:133], v[136:137]
	v_pk_fma_f32 v[252:253], v[134:135], v[134:135], v[148:149]
	v_cvt_pk_bf16_f32 v196, v134, s0
	v_cvt_pk_bf16_f32 v197, v135, s0
	v_add_f32_dpp v250, v250, v250 quad_perm:[2,3,0,1] row_mask:0xf bank_mask:0xf
	v_add_f32_dpp v251, v251, v251 quad_perm:[2,3,0,1] row_mask:0xf bank_mask:0xf
	v_add_f32_dpp v252, v252, v252 quad_perm:[2,3,0,1] row_mask:0xf bank_mask:0xf
	v_add_f32_dpp v253, v253, v253 quad_perm:[2,3,0,1] row_mask:0xf bank_mask:0xf
	global_store_short v131, v196, s[20:21] offset:-4096
	global_store_short v131, v197, s[20:21]
	v_add_f32_dpp v250, v250, v250 row_half_mirror row_mask:0xf bank_mask:0xf
	v_add_f32_dpp v251, v251, v251 row_half_mirror row_mask:0xf bank_mask:0xf
	v_add_f32_dpp v252, v252, v252 row_half_mirror row_mask:0xf bank_mask:0xf
	v_add_f32_dpp v253, v253, v253 row_half_mirror row_mask:0xf bank_mask:0xf
	v_add_f32_dpp v250, v250, v250 row_mirror row_mask:0xf bank_mask:0xf
	v_add_f32_dpp v251, v251, v251 row_mirror row_mask:0xf bank_mask:0xf
	v_add_f32_dpp v252, v252, v252 row_mirror row_mask:0xf bank_mask:0xf
	v_add_f32_dpp v253, v253, v253 row_mirror row_mask:0xf bank_mask:0xf
	s_and_saveexec_b64 s[2:3], s[8:9]
	ds_write_b128 v190, v[250:253] offset:224
	s_or_b64 exec, exec, s[2:3]
	s_mov_b64 s[2:3], 0

.LBB0_536:
	s_nop 3
	ds_read_b128 v[66:69], v248 offset:32768
	ds_read_b128 v[130:133], v247 offset:32768
	v_add_u32_e32 v145, s79, v249
	v_add_u32_e32 v70, v145, v243
	ds_read_b128 v[70:73], v70
	v_add_u32_e32 v134, v145, v245
	ds_read_b128 v[134:137], v134
	s_waitcnt lgkmcnt(1)
	v_mfma_f32_32x32x16_bf16 v[66:81], v[66:69], v[70:73], 0
	s_waitcnt lgkmcnt(0)
	v_mfma_f32_32x32x16_bf16 v[66:81], v[130:133], v[134:137], v[66:81]
	ds_read_b128 v[130:133], v242 offset:32768
	v_add_u32_e32 v134, v145, v241
	ds_read_b128 v[134:137], v134
	s_waitcnt lgkmcnt(0)
	v_mfma_f32_32x32x16_bf16 v[66:81], v[130:133], v[134:137], v[66:81]
	ds_read_b128 v[130:133], v238 offset:32768
	v_add_u32_e32 v134, v145, v226
	ds_read_b128 v[134:137], v134
	s_waitcnt lgkmcnt(0)
	v_mfma_f32_32x32x16_bf16 v[66:81], v[130:133], v[134:137], v[66:81]
	ds_read_b128 v[130:133], v224 offset:32768
	v_add_u32_e32 v134, v145, v223
	ds_read_b128 v[134:137], v134
	s_waitcnt lgkmcnt(0)
	v_mfma_f32_32x32x16_bf16 v[66:81], v[130:133], v[134:137], v[66:81]
	ds_read_b128 v[130:133], v227 offset:32768
	v_add_u32_e32 v134, v145, v225
	ds_read_b128 v[134:137], v134
	s_waitcnt lgkmcnt(0)
	v_mfma_f32_32x32x16_bf16 v[66:81], v[130:133], v[134:137], v[66:81]
	ds_read_b128 v[130:133], v240 offset:32768
	v_add_u32_e32 v134, v145, v239
	ds_read_b128 v[134:137], v134
	s_waitcnt lgkmcnt(0)
	v_mfma_f32_32x32x16_bf16 v[66:81], v[130:133], v[134:137], v[66:81]
	ds_read_b128 v[130:133], v246 offset:32768
	v_add_u32_e32 v134, v145, v244
	ds_read_b128 v[134:137], v134
	v_or_b32_e32 v145, s44, v221
	s_waitcnt lgkmcnt(0)
	v_mfma_f32_32x32x16_bf16 v[66:81], v[130:133], v[134:137], v[66:81]
	v_lshl_add_u32 v131, v145, 2, 0
	v_add_u32_e32 v131, 0x20200, v131
	ds_read_b32 v148, v131
	ds_read_b128 v[196:199], v204
	ds_read_b128 v[250:253], v204 offset:32
	v_xnor_b32_e32 v130, s4, v145
	s_waitcnt lgkmcnt(1)
	v_sub_f32_e32 v131, v196, v148
	v_exp_f32_e32 v131, v131
	v_cmp_le_u32_e32 vcc, v217, v130
	v_sub_f32_e32 v132, v197, v148
	v_exp_f32_e32 v132, v132
	v_cmp_le_u32_e64 s[2:3], v222, v130
	v_cndmask_b32_e32 v131, 0, v131, vcc
	v_mul_f32_e32 v134, v66, v131
	v_sub_f32_e32 v131, v198, v148
	v_exp_f32_e32 v131, v131
	v_cmp_le_u32_e32 vcc, v220, v130
	v_cndmask_b32_e64 v132, 0, v132, s[2:3]
	v_mul_f32_e32 v135, v67, v132
	v_sub_f32_e32 v132, v199, v148
	v_exp_f32_e32 v132, v132
	v_cmp_le_u32_e64 s[2:3], v218, v130
	ds_read_b128 v[196:199], v204 offset:64
	v_cndmask_b32_e32 v131, 0, v131, vcc
	v_mul_f32_e32 v136, v68, v131
	s_waitcnt lgkmcnt(1)
	v_sub_f32_e32 v131, v250, v148
	v_exp_f32_e32 v131, v131
	v_cmp_le_u32_e32 vcc, v216, v130
	v_cndmask_b32_e64 v132, 0, v132, s[2:3]
	v_mul_f32_e32 v137, v69, v132
	v_sub_f32_e32 v132, v251, v148
	v_exp_f32_e32 v132, v132
	v_cmp_le_u32_e64 s[2:3], v215, v130
	v_cndmask_b32_e32 v131, 0, v131, vcc
	v_mul_f32_e32 v70, v70, v131
	v_sub_f32_e32 v131, v252, v148
	v_exp_f32_e32 v131, v131
	v_cmp_le_u32_e32 vcc, v214, v130
	v_cndmask_b32_e64 v132, 0, v132, s[2:3]
	v_mul_f32_e32 v71, v71, v132
	v_sub_f32_e32 v132, v253, v148
	v_exp_f32_e32 v132, v132
	v_cmp_le_u32_e64 s[2:3], v210, v130
	ds_read_b128 v[250:253], v204 offset:96
	v_cndmask_b32_e32 v131, 0, v131, vcc
	v_mul_f32_e32 v72, v72, v131
	s_waitcnt lgkmcnt(1)
	v_sub_f32_e32 v131, v196, v148
	v_exp_f32_e32 v131, v131
	v_cmp_le_u32_e32 vcc, v209, v130
	v_cndmask_b32_e64 v132, 0, v132, s[2:3]
	v_mul_f32_e32 v73, v73, v132
	v_sub_f32_e32 v132, v197, v148
	v_exp_f32_e32 v132, v132
	v_cmp_le_u32_e64 s[2:3], v211, v130
	v_cndmask_b32_e32 v131, 0, v131, vcc
	v_mul_f32_e32 v74, v74, v131
	v_sub_f32_e32 v131, v198, v148
	v_exp_f32_e32 v131, v131
	v_cmp_le_u32_e32 vcc, v212, v130
	v_cndmask_b32_e64 v132, 0, v132, s[2:3]
	v_mul_f32_e32 v75, v75, v132
	v_sub_f32_e32 v132, v199, v148
	v_exp_f32_e32 v132, v132
	v_cmp_le_u32_e64 s[2:3], v213, v130
	v_cndmask_b32_e32 v131, 0, v131, vcc
	v_mul_f32_e32 v76, v76, v131
	s_waitcnt lgkmcnt(0)
	v_sub_f32_e32 v131, v250, v148
	v_exp_f32_e32 v131, v131
	v_cmp_le_u32_e32 vcc, v208, v130
	v_cndmask_b32_e64 v132, 0, v132, s[2:3]
	v_mul_f32_e32 v77, v77, v132
	v_sub_f32_e32 v132, v251, v148
	v_exp_f32_e32 v132, v132
	v_cmp_le_u32_e64 s[2:3], v207, v130
	v_cndmask_b32_e32 v131, 0, v131, vcc
	v_mul_f32_e32 v66, v78, v131
	v_sub_f32_e32 v131, v252, v148
	v_exp_f32_e32 v131, v131
	v_cmp_le_u32_e32 vcc, v206, v130
	v_cndmask_b32_e64 v132, 0, v132, s[2:3]
	v_mul_f32_e32 v67, v79, v132
	v_sub_f32_e32 v132, v253, v148
	v_exp_f32_e32 v132, v132
	v_cmp_le_u32_e64 s[2:3], v205, v130
	v_cndmask_b32_e32 v131, 0, v131, vcc
	v_mul_f32_e32 v68, v80, v131
	v_cndmask_b32_e64 v132, 0, v132, s[2:3]
	v_mul_f32_e32 v69, v81, v132
	s_and_b64 vcc, exec, s[6:7]
	s_cbranch_vccnz .LBB0_540
	v_add_f32_e32 v78, 0, v134
	v_add_f32_e32 v78, v135, v78
	v_add_f32_e32 v78, v136, v78
	v_add_f32_e32 v78, v137, v78
	v_add_f32_e32 v78, v70, v78
	v_add_f32_e32 v78, v71, v78
	v_add_f32_e32 v78, v72, v78
	v_add_f32_e32 v78, v73, v78
	v_add_f32_e32 v78, v74, v78
	v_add_f32_e32 v78, v75, v78
	v_add_f32_e32 v78, v76, v78
	v_add_f32_e32 v78, v77, v78
	v_add_f32_e32 v78, v66, v78
	v_add_f32_e32 v78, v67, v78
	v_add_f32_e32 v78, v68, v78
	v_add_f32_e32 v78, v69, v78
	ds_bpermute_b32 v79, v157, v78
	s_and_saveexec_b64 s[2:3], s[10:11]
	s_cbranch_execz .LBB0_539
	v_readlane_b32 s10, v254, 52
	s_waitcnt lgkmcnt(0)
	v_add_f32_e32 v78, v78, v79
	v_lshl_add_u32 v79, v145, 2, s10
	ds_write_b32 v79, v78

.LBB0_561:
	s_waitcnt vmcnt(0)
	v_add_u32_e32 v242, v177, v164
	v_lshlrev_b32_e32 v200, 16, v94
	v_and_b32_e32 v201, 0xffff0000, v94
	v_lshlrev_b32_e32 v202, 16, v95
	v_and_b32_e32 v203, 0xffff0000, v95
	v_pk_add_f32 v[200:201], v[66:67], v[200:201]
	v_pk_add_f32 v[202:203], v[68:69], v[202:203]
	v_add_u32_e32 v240, 0x41000, v144
	v_add_u32_e32 v241, 0x43000, v144
	v_pk_mul_f32 v[220:221], v[200:201], v[200:201]
	v_pk_mul_f32 v[222:223], v[202:203], v[202:203]
	v_cvt_pk_bf16_f32 v238, v200, s0
	v_cvt_pk_bf16_f32 v239, v201, s0
	v_mov_b32_dpp v224, v220 quad_perm:[1,0,3,2] row_mask:0xf bank_mask:0xf
	v_mov_b32_dpp v225, v221 quad_perm:[1,0,3,2] row_mask:0xf bank_mask:0xf
	v_mov_b32_dpp v226, v222 quad_perm:[1,0,3,2] row_mask:0xf bank_mask:0xf
	v_mov_b32_dpp v227, v223 quad_perm:[1,0,3,2] row_mask:0xf bank_mask:0xf
	global_store_short v240, v238, s[20:21] offset:-4096
	global_store_short v240, v239, s[20:21]
	v_pk_fma_f32 v[220:221], v[200:201], v[200:201], v[224:225]
	v_pk_fma_f32 v[222:223], v[202:203], v[202:203], v[226:227]
	v_cvt_pk_bf16_f32 v238, v202, s0
	v_cvt_pk_bf16_f32 v239, v203, s0
	v_add_f32_dpp v220, v220, v220 quad_perm:[2,3,0,1] row_mask:0xf bank_mask:0xf
	v_add_f32_dpp v221, v221, v221 quad_perm:[2,3,0,1] row_mask:0xf bank_mask:0xf
	v_add_f32_dpp v222, v222, v222 quad_perm:[2,3,0,1] row_mask:0xf bank_mask:0xf
	v_add_f32_dpp v223, v223, v223 quad_perm:[2,3,0,1] row_mask:0xf bank_mask:0xf
	global_store_short v241, v238, s[20:21] offset:-4096
	global_store_short v241, v239, s[20:21]
	v_add_f32_dpp v220, v220, v220 row_half_mirror row_mask:0xf bank_mask:0xf
	v_add_f32_dpp v221, v221, v221 row_half_mirror row_mask:0xf bank_mask:0xf
	v_add_f32_dpp v222, v222, v222 row_half_mirror row_mask:0xf bank_mask:0xf
	v_add_f32_dpp v223, v223, v223 row_half_mirror row_mask:0xf bank_mask:0xf
	v_add_f32_dpp v220, v220, v220 row_mirror row_mask:0xf bank_mask:0xf
	v_add_f32_dpp v221, v221, v221 row_mirror row_mask:0xf bank_mask:0xf
	v_add_f32_dpp v222, v222, v222 row_mirror row_mask:0xf bank_mask:0xf
	v_add_f32_dpp v223, v223, v223 row_mirror row_mask:0xf bank_mask:0xf
	s_and_saveexec_b64 s[10:11], s[8:9]
	ds_write_b128 v242, v[220:223]
	s_or_b64 exec, exec, s[10:11]
	v_lshlrev_b32_e32 v200, 16, v96
	v_and_b32_e32 v201, 0xffff0000, v96
	v_lshlrev_b32_e32 v202, 16, v97
	v_and_b32_e32 v203, 0xffff0000, v97
	v_pk_add_f32 v[200:201], v[70:71], v[200:201]
	v_pk_add_f32 v[202:203], v[72:73], v[202:203]
	v_add_u32_e32 v240, 0x49000, v144
	v_add_u32_e32 v241, 0x4b000, v144
	v_pk_mul_f32 v[220:221], v[200:201], v[200:201]
	v_pk_mul_f32 v[222:223], v[202:203], v[202:203]
	v_cvt_pk_bf16_f32 v238, v200, s0
	v_cvt_pk_bf16_f32 v239, v201, s0
	v_mov_b32_dpp v224, v220 quad_perm:[1,0,3,2] row_mask:0xf bank_mask:0xf
	v_mov_b32_dpp v225, v221 quad_perm:[1,0,3,2] row_mask:0xf bank_mask:0xf
	v_mov_b32_dpp v226, v222 quad_perm:[1,0,3,2] row_mask:0xf bank_mask:0xf
	v_mov_b32_dpp v227, v223 quad_perm:[1,0,3,2] row_mask:0xf bank_mask:0xf
	global_store_short v240, v238, s[20:21] offset:-4096
	global_store_short v240, v239, s[20:21]
	v_pk_fma_f32 v[220:221], v[200:201], v[200:201], v[224:225]
	v_pk_fma_f32 v[222:223], v[202:203], v[202:203], v[226:227]
	v_cvt_pk_bf16_f32 v238, v202, s0
	v_cvt_pk_bf16_f32 v239, v203, s0
	v_add_f32_dpp v220, v220, v220 quad_perm:[2,3,0,1] row_mask:0xf bank_mask:0xf
	v_add_f32_dpp v221, v221, v221 quad_perm:[2,3,0,1] row_mask:0xf bank_mask:0xf
	v_add_f32_dpp v222, v222, v222 quad_perm:[2,3,0,1] row_mask:0xf bank_mask:0xf
	v_add_f32_dpp v223, v223, v223 quad_perm:[2,3,0,1] row_mask:0xf bank_mask:0xf
	global_store_short v241, v238, s[20:21] offset:-4096
	global_store_short v241, v239, s[20:21]
	v_add_f32_dpp v220, v220, v220 row_half_mirror row_mask:0xf bank_mask:0xf
	v_add_f32_dpp v221, v221, v221 row_half_mirror row_mask:0xf bank_mask:0xf
	v_add_f32_dpp v222, v222, v222 row_half_mirror row_mask:0xf bank_mask:0xf
	v_add_f32_dpp v223, v223, v223 row_half_mirror row_mask:0xf bank_mask:0xf
	v_add_f32_dpp v220, v220, v220 row_mirror row_mask:0xf bank_mask:0xf
	v_add_f32_dpp v221, v221, v221 row_mirror row_mask:0xf bank_mask:0xf
	v_add_f32_dpp v222, v222, v222 row_mirror row_mask:0xf bank_mask:0xf
	v_add_f32_dpp v223, v223, v223 row_mirror row_mask:0xf bank_mask:0xf
	s_and_saveexec_b64 s[10:11], s[8:9]
	ds_write_b128 v242, v[220:223] offset:32
	s_or_b64 exec, exec, s[10:11]
	v_lshlrev_b32_e32 v200, 16, v90
	v_and_b32_e32 v201, 0xffff0000, v90
	v_lshlrev_b32_e32 v202, 16, v91
	v_and_b32_e32 v203, 0xffff0000, v91
	v_pk_add_f32 v[200:201], v[74:75], v[200:201]
	v_pk_add_f32 v[202:203], v[76:77], v[202:203]
	v_add_u32_e32 v240, 0x51000, v144
	v_add_u32_e32 v241, 0x53000, v144
	v_pk_mul_f32 v[220:221], v[200:201], v[200:201]
	v_pk_mul_f32 v[222:223], v[202:203], v[202:203]
	v_cvt_pk_bf16_f32 v238, v200, s0
	v_cvt_pk_bf16_f32 v239, v201, s0
	v_mov_b32_dpp v224, v220 quad_perm:[1,0,3,2] row_mask:0xf bank_mask:0xf
	v_mov_b32_dpp v225, v221 quad_perm:[1,0,3,2] row_mask:0xf bank_mask:0xf
	v_mov_b32_dpp v226, v222 quad_perm:[1,0,3,2] row_mask:0xf bank_mask:0xf
	v_mov_b32_dpp v227, v223 quad_perm:[1,0,3,2] row_mask:0xf bank_mask:0xf
	global_store_short v240, v238, s[20:21] offset:-4096
	global_store_short v240, v239, s[20:21]
	v_pk_fma_f32 v[220:221], v[200:201], v[200:201], v[224:225]
	v_pk_fma_f32 v[222:223], v[202:203], v[202:203], v[226:227]
	v_cvt_pk_bf16_f32 v238, v202, s0
	v_cvt_pk_bf16_f32 v239, v203, s0
	v_add_f32_dpp v220, v220, v220 quad_perm:[2,3,0,1] row_mask:0xf bank_mask:0xf
	v_add_f32_dpp v221, v221, v221 quad_perm:[2,3,0,1] row_mask:0xf bank_mask:0xf
	v_add_f32_dpp v222, v222, v222 quad_perm:[2,3,0,1] row_mask:0xf bank_mask:0xf
	v_add_f32_dpp v223, v223, v223 quad_perm:[2,3,0,1] row_mask:0xf bank_mask:0xf
	global_store_short v241, v238, s[20:21] offset:-4096
	global_store_short v241, v239, s[20:21]
	v_add_f32_dpp v220, v220, v220 row_half_mirror row_mask:0xf bank_mask:0xf
	v_add_f32_dpp v221, v221, v221 row_half_mirror row_mask:0xf bank_mask:0xf
	v_add_f32_dpp v222, v222, v222 row_half_mirror row_mask:0xf bank_mask:0xf
	v_add_f32_dpp v223, v223, v223 row_half_mirror row_mask:0xf bank_mask:0xf
	v_add_f32_dpp v220, v220, v220 row_mirror row_mask:0xf bank_mask:0xf
	v_add_f32_dpp v221, v221, v221 row_mirror row_mask:0xf bank_mask:0xf
	v_add_f32_dpp v222, v222, v222 row_mirror row_mask:0xf bank_mask:0xf
	v_add_f32_dpp v223, v223, v223 row_mirror row_mask:0xf bank_mask:0xf
	s_and_saveexec_b64 s[10:11], s[8:9]
	ds_write_b128 v242, v[220:223] offset:64
	s_or_b64 exec, exec, s[10:11]
	v_lshlrev_b32_e32 v200, 16, v92
	v_and_b32_e32 v201, 0xffff0000, v92
	v_lshlrev_b32_e32 v202, 16, v93
	v_and_b32_e32 v203, 0xffff0000, v93
	v_pk_add_f32 v[200:201], v[78:79], v[200:201]
	v_pk_add_f32 v[202:203], v[80:81], v[202:203]
	v_add_u32_e32 v240, 0x59000, v144
	v_add_u32_e32 v241, 0x5b000, v144
	v_pk_mul_f32 v[220:221], v[200:201], v[200:201]
	v_pk_mul_f32 v[222:223], v[202:203], v[202:203]
	v_cvt_pk_bf16_f32 v238, v200, s0
	v_cvt_pk_bf16_f32 v239, v201, s0
	v_mov_b32_dpp v224, v220 quad_perm:[1,0,3,2] row_mask:0xf bank_mask:0xf
	v_mov_b32_dpp v225, v221 quad_perm:[1,0,3,2] row_mask:0xf bank_mask:0xf
	v_mov_b32_dpp v226, v222 quad_perm:[1,0,3,2] row_mask:0xf bank_mask:0xf
	v_mov_b32_dpp v227, v223 quad_perm:[1,0,3,2] row_mask:0xf bank_mask:0xf
	global_store_short v240, v238, s[20:21] offset:-4096
	global_store_short v240, v239, s[20:21]
	v_pk_fma_f32 v[220:221], v[200:201], v[200:201], v[224:225]
	v_pk_fma_f32 v[222:223], v[202:203], v[202:203], v[226:227]
	v_cvt_pk_bf16_f32 v238, v202, s0
	v_cvt_pk_bf16_f32 v239, v203, s0
	v_add_f32_dpp v220, v220, v220 quad_perm:[2,3,0,1] row_mask:0xf bank_mask:0xf
	v_add_f32_dpp v221, v221, v221 quad_perm:[2,3,0,1] row_mask:0xf bank_mask:0xf
	v_add_f32_dpp v222, v222, v222 quad_perm:[2,3,0,1] row_mask:0xf bank_mask:0xf
	v_add_f32_dpp v223, v223, v223 quad_perm:[2,3,0,1] row_mask:0xf bank_mask:0xf
	global_store_short v241, v238, s[20:21] offset:-4096
	global_store_short v241, v239, s[20:21]
	v_add_f32_dpp v220, v220, v220 row_half_mirror row_mask:0xf bank_mask:0xf
	v_add_f32_dpp v221, v221, v221 row_half_mirror row_mask:0xf bank_mask:0xf
	v_add_f32_dpp v222, v222, v222 row_half_mirror row_mask:0xf bank_mask:0xf
	v_add_f32_dpp v223, v223, v223 row_half_mirror row_mask:0xf bank_mask:0xf
	v_add_f32_dpp v220, v220, v220 row_mirror row_mask:0xf bank_mask:0xf
	v_add_f32_dpp v221, v221, v221 row_mirror row_mask:0xf bank_mask:0xf
	v_add_f32_dpp v222, v222, v222 row_mirror row_mask:0xf bank_mask:0xf
	v_add_f32_dpp v223, v223, v223 row_mirror row_mask:0xf bank_mask:0xf
	s_and_saveexec_b64 s[10:11], s[8:9]
	ds_write_b128 v242, v[220:223] offset:96
	s_or_b64 exec, exec, s[10:11]
	s_branch .LBB0_550

.LBB0_571:
	s_waitcnt vmcnt(15)
	v_add_u32_e32 v242, v177, v164
	v_lshlrev_b32_e32 v200, 16, v86
	v_and_b32_e32 v201, 0xffff0000, v86
	v_lshlrev_b32_e32 v202, 16, v87
	v_and_b32_e32 v203, 0xffff0000, v87
	v_pk_add_f32 v[200:201], v[66:67], v[200:201]
	v_pk_add_f32 v[202:203], v[68:69], v[202:203]
	v_add_u32_e32 v240, 0x61000, v144
	v_add_u32_e32 v241, 0x63000, v144
	v_pk_mul_f32 v[220:221], v[200:201], v[200:201]
	v_pk_mul_f32 v[222:223], v[202:203], v[202:203]
	v_cvt_pk_bf16_f32 v238, v200, s0
	v_cvt_pk_bf16_f32 v239, v201, s0
	v_mov_b32_dpp v224, v220 quad_perm:[1,0,3,2] row_mask:0xf bank_mask:0xf
	v_mov_b32_dpp v225, v221 quad_perm:[1,0,3,2] row_mask:0xf bank_mask:0xf
	v_mov_b32_dpp v226, v222 quad_perm:[1,0,3,2] row_mask:0xf bank_mask:0xf
	v_mov_b32_dpp v227, v223 quad_perm:[1,0,3,2] row_mask:0xf bank_mask:0xf
	global_store_short v240, v238, s[20:21] offset:-4096
	global_store_short v240, v239, s[20:21]
	v_pk_fma_f32 v[220:221], v[200:201], v[200:201], v[224:225]
	v_pk_fma_f32 v[222:223], v[202:203], v[202:203], v[226:227]
	v_cvt_pk_bf16_f32 v238, v202, s0
	v_cvt_pk_bf16_f32 v239, v203, s0
	v_add_f32_dpp v220, v220, v220 quad_perm:[2,3,0,1] row_mask:0xf bank_mask:0xf
	v_add_f32_dpp v221, v221, v221 quad_perm:[2,3,0,1] row_mask:0xf bank_mask:0xf
	v_add_f32_dpp v222, v222, v222 quad_perm:[2,3,0,1] row_mask:0xf bank_mask:0xf
	v_add_f32_dpp v223, v223, v223 quad_perm:[2,3,0,1] row_mask:0xf bank_mask:0xf
	global_store_short v241, v238, s[20:21] offset:-4096
	global_store_short v241, v239, s[20:21]
	v_add_f32_dpp v220, v220, v220 row_half_mirror row_mask:0xf bank_mask:0xf
	v_add_f32_dpp v221, v221, v221 row_half_mirror row_mask:0xf bank_mask:0xf
	v_add_f32_dpp v222, v222, v222 row_half_mirror row_mask:0xf bank_mask:0xf
	v_add_f32_dpp v223, v223, v223 row_half_mirror row_mask:0xf bank_mask:0xf
	v_add_f32_dpp v220, v220, v220 row_mirror row_mask:0xf bank_mask:0xf
	v_add_f32_dpp v221, v221, v221 row_mirror row_mask:0xf bank_mask:0xf
	v_add_f32_dpp v222, v222, v222 row_mirror row_mask:0xf bank_mask:0xf
	v_add_f32_dpp v223, v223, v223 row_mirror row_mask:0xf bank_mask:0xf
	s_and_saveexec_b64 s[10:11], s[8:9]
	ds_write_b128 v242, v[220:223] offset:128
	s_or_b64 exec, exec, s[10:11]
	v_lshlrev_b32_e32 v200, 16, v88
	v_and_b32_e32 v201, 0xffff0000, v88
	v_lshlrev_b32_e32 v202, 16, v89
	v_and_b32_e32 v203, 0xffff0000, v89
	v_pk_add_f32 v[200:201], v[70:71], v[200:201]
	v_pk_add_f32 v[202:203], v[72:73], v[202:203]
	v_add_u32_e32 v240, 0x69000, v144
	v_add_u32_e32 v241, 0x6b000, v144
	v_pk_mul_f32 v[220:221], v[200:201], v[200:201]
	v_pk_mul_f32 v[222:223], v[202:203], v[202:203]
	v_cvt_pk_bf16_f32 v238, v200, s0
	v_cvt_pk_bf16_f32 v239, v201, s0
	v_mov_b32_dpp v224, v220 quad_perm:[1,0,3,2] row_mask:0xf bank_mask:0xf
	v_mov_b32_dpp v225, v221 quad_perm:[1,0,3,2] row_mask:0xf bank_mask:0xf
	v_mov_b32_dpp v226, v222 quad_perm:[1,0,3,2] row_mask:0xf bank_mask:0xf
	v_mov_b32_dpp v227, v223 quad_perm:[1,0,3,2] row_mask:0xf bank_mask:0xf
	global_store_short v240, v238, s[20:21] offset:-4096
	global_store_short v240, v239, s[20:21]
	v_pk_fma_f32 v[220:221], v[200:201], v[200:201], v[224:225]
	v_pk_fma_f32 v[222:223], v[202:203], v[202:203], v[226:227]
	v_cvt_pk_bf16_f32 v238, v202, s0
	v_cvt_pk_bf16_f32 v239, v203, s0
	v_add_f32_dpp v220, v220, v220 quad_perm:[2,3,0,1] row_mask:0xf bank_mask:0xf
	v_add_f32_dpp v221, v221, v221 quad_perm:[2,3,0,1] row_mask:0xf bank_mask:0xf
	v_add_f32_dpp v222, v222, v222 quad_perm:[2,3,0,1] row_mask:0xf bank_mask:0xf
	v_add_f32_dpp v223, v223, v223 quad_perm:[2,3,0,1] row_mask:0xf bank_mask:0xf
	global_store_short v241, v238, s[20:21] offset:-4096
	global_store_short v241, v239, s[20:21]
	v_add_f32_dpp v220, v220, v220 row_half_mirror row_mask:0xf bank_mask:0xf
	v_add_f32_dpp v221, v221, v221 row_half_mirror row_mask:0xf bank_mask:0xf
	v_add_f32_dpp v222, v222, v222 row_half_mirror row_mask:0xf bank_mask:0xf
	v_add_f32_dpp v223, v223, v223 row_half_mirror row_mask:0xf bank_mask:0xf
	v_add_f32_dpp v220, v220, v220 row_mirror row_mask:0xf bank_mask:0xf
	v_add_f32_dpp v221, v221, v221 row_mirror row_mask:0xf bank_mask:0xf
	v_add_f32_dpp v222, v222, v222 row_mirror row_mask:0xf bank_mask:0xf
	v_add_f32_dpp v223, v223, v223 row_mirror row_mask:0xf bank_mask:0xf
	s_and_saveexec_b64 s[10:11], s[8:9]
	ds_write_b128 v242, v[220:223] offset:160
	s_or_b64 exec, exec, s[10:11]
	v_lshlrev_b32_e32 v200, 16, v82
	v_and_b32_e32 v201, 0xffff0000, v82
	v_lshlrev_b32_e32 v202, 16, v83
	v_and_b32_e32 v203, 0xffff0000, v83
	v_pk_add_f32 v[200:201], v[74:75], v[200:201]
	v_pk_add_f32 v[202:203], v[76:77], v[202:203]
	v_add_u32_e32 v240, 0x71000, v144
	v_add_u32_e32 v241, 0x73000, v144
	v_pk_mul_f32 v[220:221], v[200:201], v[200:201]
	v_pk_mul_f32 v[222:223], v[202:203], v[202:203]
	v_cvt_pk_bf16_f32 v238, v200, s0
	v_cvt_pk_bf16_f32 v239, v201, s0
	v_mov_b32_dpp v224, v220 quad_perm:[1,0,3,2] row_mask:0xf bank_mask:0xf
	v_mov_b32_dpp v225, v221 quad_perm:[1,0,3,2] row_mask:0xf bank_mask:0xf
	v_mov_b32_dpp v226, v222 quad_perm:[1,0,3,2] row_mask:0xf bank_mask:0xf
	v_mov_b32_dpp v227, v223 quad_perm:[1,0,3,2] row_mask:0xf bank_mask:0xf
	global_store_short v240, v238, s[20:21] offset:-4096
	global_store_short v240, v239, s[20:21]
	v_pk_fma_f32 v[220:221], v[200:201], v[200:201], v[224:225]
	v_pk_fma_f32 v[222:223], v[202:203], v[202:203], v[226:227]
	v_cvt_pk_bf16_f32 v238, v202, s0
	v_cvt_pk_bf16_f32 v239, v203, s0
	v_add_f32_dpp v220, v220, v220 quad_perm:[2,3,0,1] row_mask:0xf bank_mask:0xf
	v_add_f32_dpp v221, v221, v221 quad_perm:[2,3,0,1] row_mask:0xf bank_mask:0xf
	v_add_f32_dpp v222, v222, v222 quad_perm:[2,3,0,1] row_mask:0xf bank_mask:0xf
	v_add_f32_dpp v223, v223, v223 quad_perm:[2,3,0,1] row_mask:0xf bank_mask:0xf
	global_store_short v241, v238, s[20:21] offset:-4096
	global_store_short v241, v239, s[20:21]
	v_add_f32_dpp v220, v220, v220 row_half_mirror row_mask:0xf bank_mask:0xf
	v_add_f32_dpp v221, v221, v221 row_half_mirror row_mask:0xf bank_mask:0xf
	v_add_f32_dpp v222, v222, v222 row_half_mirror row_mask:0xf bank_mask:0xf
	v_add_f32_dpp v223, v223, v223 row_half_mirror row_mask:0xf bank_mask:0xf
	v_add_f32_dpp v220, v220, v220 row_mirror row_mask:0xf bank_mask:0xf
	v_add_f32_dpp v221, v221, v221 row_mirror row_mask:0xf bank_mask:0xf
	v_add_f32_dpp v222, v222, v222 row_mirror row_mask:0xf bank_mask:0xf
	v_add_f32_dpp v223, v223, v223 row_mirror row_mask:0xf bank_mask:0xf
	s_and_saveexec_b64 s[10:11], s[8:9]
	ds_write_b128 v242, v[220:223] offset:192
	s_or_b64 exec, exec, s[10:11]
	v_lshlrev_b32_e32 v200, 16, v84
	v_and_b32_e32 v201, 0xffff0000, v84
	v_lshlrev_b32_e32 v202, 16, v85
	v_and_b32_e32 v203, 0xffff0000, v85
	v_pk_add_f32 v[200:201], v[78:79], v[200:201]
	v_pk_add_f32 v[202:203], v[80:81], v[202:203]
	v_add_u32_e32 v240, 0x79000, v144
	v_add_u32_e32 v241, 0x7b000, v144
	v_pk_mul_f32 v[220:221], v[200:201], v[200:201]
	v_pk_mul_f32 v[222:223], v[202:203], v[202:203]
	v_cvt_pk_bf16_f32 v238, v200, s0
	v_cvt_pk_bf16_f32 v239, v201, s0
	v_mov_b32_dpp v224, v220 quad_perm:[1,0,3,2] row_mask:0xf bank_mask:0xf
	v_mov_b32_dpp v225, v221 quad_perm:[1,0,3,2] row_mask:0xf bank_mask:0xf
	v_mov_b32_dpp v226, v222 quad_perm:[1,0,3,2] row_mask:0xf bank_mask:0xf
	v_mov_b32_dpp v227, v223 quad_perm:[1,0,3,2] row_mask:0xf bank_mask:0xf
	global_store_short v240, v238, s[20:21] offset:-4096
	global_store_short v240, v239, s[20:21]
	v_pk_fma_f32 v[220:221], v[200:201], v[200:201], v[224:225]
	v_pk_fma_f32 v[222:223], v[202:203], v[202:203], v[226:227]
	v_cvt_pk_bf16_f32 v238, v202, s0
	v_cvt_pk_bf16_f32 v239, v203, s0
	v_add_f32_dpp v220, v220, v220 quad_perm:[2,3,0,1] row_mask:0xf bank_mask:0xf
	v_add_f32_dpp v221, v221, v221 quad_perm:[2,3,0,1] row_mask:0xf bank_mask:0xf
	v_add_f32_dpp v222, v222, v222 quad_perm:[2,3,0,1] row_mask:0xf bank_mask:0xf
	v_add_f32_dpp v223, v223, v223 quad_perm:[2,3,0,1] row_mask:0xf bank_mask:0xf
	global_store_short v241, v238, s[20:21] offset:-4096
	global_store_short v241, v239, s[20:21]
	v_add_f32_dpp v220, v220, v220 row_half_mirror row_mask:0xf bank_mask:0xf
	v_add_f32_dpp v221, v221, v221 row_half_mirror row_mask:0xf bank_mask:0xf
	v_add_f32_dpp v222, v222, v222 row_half_mirror row_mask:0xf bank_mask:0xf
	v_add_f32_dpp v223, v223, v223 row_half_mirror row_mask:0xf bank_mask:0xf
	v_add_f32_dpp v220, v220, v220 row_mirror row_mask:0xf bank_mask:0xf
	v_add_f32_dpp v221, v221, v221 row_mirror row_mask:0xf bank_mask:0xf
	v_add_f32_dpp v222, v222, v222 row_mirror row_mask:0xf bank_mask:0xf
	v_add_f32_dpp v223, v223, v223 row_mirror row_mask:0xf bank_mask:0xf
	s_and_saveexec_b64 s[10:11], s[8:9]
	ds_write_b128 v242, v[220:223] offset:224
	s_or_b64 exec, exec, s[10:11]
	s_branch .LBB0_554
